# v086 + two more deferral windows: the idle tails of the two layer-0 pass_post row passes (blocks 64..255) convert down-L0 / part of up-L0 weights and the layer-1 in/out projection weights; P0 now conv
# speedup vs baseline: 1.0029x; 1.0029x over previous
; #define LAS __attribute__((address_space(3)))
; __device__ __forceinline__ void p0_weights(KAP a, LAS unsigned char* lds, int gw, int NGW, int wave, int lane) {
;     LAS float* scr = (LAS float*)(lds + wave * 8704);
;     unsigned char* ws = a->ws;
;     constexpr int I_TOTAL = (2048 / 64) * (2624 / 32) + (512 / 64) * (1536 / 32) + (512 / 64) * (2048 / 32) + 2 * (2048 / 64) * (2048 / 32) + (2048 / 64) * (4608 / 32)
;                           + 4 * (2048 / 64) * (DFF / 32) + 2 * (DFF / 64) * (2048 / 32);
;     for (int item = gw; item < I_TOTAL; item += NGW) {
;         int it = item;
;         if (conv_matrix(it, a->in[13], 2048, 2624, (bf16*)(ws + WS_WIN0), 0, scr, lane)) continue;
;         if (conv_matrix(it, a->in[19], 512, 1536, (bf16*)(ws + WS_WUQ), 0, scr, lane, 0.07216878364870322f * 1.4426950408889634f)) continue;
;         if (conv_matrix(it, a->in[20], 512, 2048, (bf16*)(ws + WS_WUKV), 0, scr, lane)) continue;
;         if (conv_matrix(it, a->in[14], 2048, 2048, (bf16*)(ws + WS_WOUT0), 0, scr, lane)) continue;
;         if (conv_matrix(it, a->in[21], 2048, 4608, (bf16*)(ws + WS_WIN1), 0, scr, lane)) continue;
;         if (conv_matrix(it, a->in[22], 2048, 2048, (bf16*)(ws + WS_WOUT1), 0, scr, lane)) continue;
;         if (conv_matrix(it, a->in[10], 2048, DFF, (bf16*)(ws + WS_WGU), 1, scr, lane)) continue;
;         if (conv_matrix(it, a->in[10] + (size_t)2048 * DFF, 2048, DFF, (bf16*)(ws + WS_WGU + 44 * MiB), 1, scr, lane)) continue;
;         if (conv_matrix(it, a->in[11], 2048, DFF, (bf16*)(ws + WS_WGU), 2, scr, lane)) continue;
;         if (conv_matrix(it, a->in[11] + (size_t)2048 * DFF, 2048, DFF, (bf16*)(ws + WS_WGU + 44 * MiB), 2, scr, lane)) continue;
;         if (conv_matrix(it, a->in[12], DFF, 2048, (bf16*)(ws + WS_WD), 0, scr, lane)) continue;
;         conv_matrix(it, a->in[12] + (size_t)2048 * DFF, DFF, 2048, (bf16*)(ws + WS_WD + 22 * MiB), 0, scr, lane);
;     }
; }
.LBB0_36:
	v_mbcnt_lo_u32_b32 v2, -1, 0
	v_mbcnt_hi_u32_b32 v2, -1, v2
	s_lshl_b32 s5, s87, 3
	v_add_u32_e32 v0, s93, v2
	s_lshl_b32 s33, s74, 3
	v_readfirstlane_b32 s4, v0
	s_ashr_i32 s6, s4, 6
	s_add_i32 s99, s6, s5
	v_writelane_b32 v253, s5, 2
	s_mov_b64 s[4:5], s[0:1]
	s_cmp_gt_i32 s99, 0x39bf
	s_cbranch_scc1 .LBB0_119
	s_load_dwordx2 s[8:9], s[4:5], 0xf0
	v_bfe_u32 v0, v2, 5, 1
	v_and_b32_e32 v28, 31, v2
	v_bfe_u32 v1, v2, 3, 3
	v_lshlrev_b32_e32 v2, 3, v2
	v_and_b32_e32 v2, 56, v2
	v_mov_b32_e32 v3, 0
	v_mul_u32_u24_e32 v6, 0x84, v2
	v_lshlrev_b32_e32 v2, 1, v2
	s_mul_i32 s10, s6, 0x2200
	s_waitcnt lgkmcnt(0)
	v_lshl_add_u64 v[22:23], s[8:9], 0, v[2:3]
	s_mov_b64 s[6:7], 0x100000
	s_add_i32 s11, s10, 0
	v_lshl_add_u64 v[4:5], v[22:23], 0, s[6:7]
	v_lshlrev_b32_e32 v2, 2, v1
	s_mov_b64 s[6:7], 0xc00000
	v_add3_u32 v44, s11, v6, v2
	v_lshl_add_u64 v[6:7], v[22:23], 0, s[6:7]
	s_mov_b64 s[6:7], 0xe00000
	v_lshl_add_u64 v[8:9], v[22:23], 0, s[6:7]
	s_mov_b64 s[6:7], 0x1000000
	v_lshl_add_u64 v[10:11], v[22:23], 0, s[6:7]
	s_mov_b64 s[6:7], 0x1800000
	v_lshl_add_u64 v[12:13], v[22:23], 0, s[6:7]
	s_mov_b64 s[6:7], 0x2a00000
	v_lshl_add_u64 v[14:15], v[22:23], 0, s[6:7]
	s_mov_b64 s[6:7], 0x3200000
	v_lshl_add_u64 v[16:17], v[22:23], 0, s[6:7]
	s_mov_b64 s[6:7], 0x5e00000
	v_lshl_add_u64 v[18:19], v[22:23], 0, s[6:7]
	s_mov_b64 s[6:7], 0x8a00000
	v_mul_u32_u24_e32 v2, 0x84, v0
	v_lshl_add_u64 v[20:21], v[22:23], 0, s[6:7]
	s_mov_b64 s[6:7], 0xa000000
	v_or_b32_e32 v2, s10, v2
	v_lshlrev_b32_e32 v24, 2, v28
	v_or_b32_e32 v45, 8, v1
	v_or_b32_e32 v46, 16, v1
	v_or_b32_e32 v47, 24, v1
	v_lshl_add_u64 v[22:23], v[22:23], 0, s[6:7]
	v_add3_u32 v48, v2, v24, 0
	v_mov_b32_e32 v25, v3
	v_or_b32_e32 v49, 14, v0
	v_or_b32_e32 v50, 12, v0
	v_or_b32_e32 v51, 10, v0
	v_or_b32_e32 v52, 8, v0
	v_or_b32_e32 v53, 6, v0
	v_or_b32_e32 v54, 4, v0
	v_or_b32_e32 v55, 2, v0
	v_or_b32_e32 v26, 0x2c00000, v24
	v_mov_b32_e32 v27, v3
	s_movk_i32 s23, 0x2900
	s_movk_i32 s24, 0x7fff
	s_mov_b32 s25, 0xffff0000
	s_movk_i32 s26, 0x1800
	s_movk_i32 s27, 0x4800
	s_movk_i32 s28, 0x1600
	s_movk_i32 s29, 0x5800
	s_mov_b64 s[6:7], 0x2c00000
	v_lshlrev_b32_e32 v2, 2, v28
	v_mov_b32_e32 v56, 0x4800
	v_mov_b32_e32 v57, 0x5800
	s_branch .LBB0_39
.LBB0_38:
	s_add_i32 s99, s99, s33
	s_cmp_lt_i32 s99, 0x39c0
	s_cbranch_scc0 .LBB0_119
.LBB0_39:
	s_mov_b32 s22, s99
	s_cmp_ge_i32 s99, 0x15c0
	s_cselect_b32 s98, 0x1a00, 0
	s_add_i32 s22, s22, s98
	s_cmp_ge_i32 s99, 0x2bc0
	s_cselect_b32 s98, 0x1600, 0
	s_add_i32 s22, s22, s98
	s_cmpk_gt_i32 s22, 0xa3f
	s_waitcnt lgkmcnt(0)
	s_cselect_b64 s[8:9], -1, 0
	s_cmpk_lt_i32 s22, 0xa40
	s_mov_b64 s[10:11], -1
	s_cbranch_scc0 .LBB0_42
	s_andn2_b64 vcc, exec, s[10:11]
	s_cbranch_vccz .LBB0_43

; #define LAS __attribute__((address_space(3)))
; __device__ __forceinline__ void p0_weights(KAP a, LAS unsigned char* lds, int gw, int NGW, int wave, int lane) {
;     LAS float* scr = (LAS float*)(lds + wave * 8704);
;     unsigned char* ws = a->ws;
;     constexpr int I_TOTAL = (2048 / 64) * (2624 / 32) + (512 / 64) * (1536 / 32) + (512 / 64) * (2048 / 32) + 2 * (2048 / 64) * (2048 / 32) + (2048 / 64) * (4608 / 32)
;                           + 4 * (2048 / 64) * (DFF / 32) + 2 * (DFF / 64) * (2048 / 32);
;     for (int item = gw; item < I_TOTAL; item += NGW) {
;         int it = item;
;         if (conv_matrix(it, a->in[13], 2048, 2624, (bf16*)(ws + WS_WIN0), 0, scr, lane)) continue;
;         if (conv_matrix(it, a->in[19], 512, 1536, (bf16*)(ws + WS_WUQ), 0, scr, lane, 0.07216878364870322f * 1.4426950408889634f)) continue;
;         if (conv_matrix(it, a->in[20], 512, 2048, (bf16*)(ws + WS_WUKV), 0, scr, lane)) continue;
;         if (conv_matrix(it, a->in[14], 2048, 2048, (bf16*)(ws + WS_WOUT0), 0, scr, lane)) continue;
;         if (conv_matrix(it, a->in[21], 2048, 4608, (bf16*)(ws + WS_WIN1), 0, scr, lane)) continue;
;         if (conv_matrix(it, a->in[22], 2048, 2048, (bf16*)(ws + WS_WOUT1), 0, scr, lane)) continue;
;         if (conv_matrix(it, a->in[10], 2048, DFF, (bf16*)(ws + WS_WGU), 1, scr, lane)) continue;
;         if (conv_matrix(it, a->in[10] + (size_t)2048 * DFF, 2048, DFF, (bf16*)(ws + WS_WGU + 44 * MiB), 1, scr, lane)) continue;
;         if (conv_matrix(it, a->in[11], 2048, DFF, (bf16*)(ws + WS_WGU), 2, scr, lane)) continue;
;         if (conv_matrix(it, a->in[11] + (size_t)2048 * DFF, 2048, DFF, (bf16*)(ws + WS_WGU + 44 * MiB), 2, scr, lane)) continue;
;         if (conv_matrix(it, a->in[12], DFF, 2048, (bf16*)(ws + WS_WD), 0, scr, lane)) continue;
;         conv_matrix(it, a->in[12] + (size_t)2048 * DFF, DFF, 2048, (bf16*)(ws + WS_WD + 22 * MiB), 0, scr, lane);
;     }
.LBB0_971:
	v_readlane_b32 s4, v254, 52
	s_nop 1
	s_cmp_lg_u32 s4, 0
	s_cbranch_scc1 .Ldp1_skip
	s_cmp_lt_u32 s87, 64
	s_cbranch_scc1 .Ldp1_skip
	s_waitcnt lgkmcnt(0)
	s_barrier
	v_mov_b32_e32 v250, v3
	v_writelane_b32 v255, s10, 10
	v_writelane_b32 v255, s12, 11
	v_writelane_b32 v255, s13, 12
	v_writelane_b32 v255, s14, 13
	v_writelane_b32 v255, s15, 14
	v_writelane_b32 v255, s22, 15
	v_writelane_b32 v255, s23, 16
	v_writelane_b32 v255, s24, 17
	v_writelane_b32 v255, s25, 18
	v_writelane_b32 v255, s26, 19
	v_writelane_b32 v255, s27, 20
	v_writelane_b32 v255, s28, 21
	v_writelane_b32 v255, s29, 22
	v_writelane_b32 v255, s31, 23
	v_writelane_b32 v255, s33, 24
.Ldp1_36:
	v_mbcnt_lo_u32_b32 v2, -1, 0
	v_mbcnt_hi_u32_b32 v2, -1, v2
	s_sub_i32 s5, s87, 64
	s_lshl_b32 s5, s5, 3
	s_add_i32 s5, s5, 0x0
	v_readlane_b32 s4, v254, 48
	s_nop 1
	v_add_u32_e32 v0, s4, v2
	s_movk_i32 s33, 0x600
	v_readfirstlane_b32 s4, v0
	s_ashr_i32 s6, s4, 6
	s_add_i32 s99, s6, s5
	s_mov_b64 s[4:5], s[0:1]
	s_cmp_gt_i32 s99, 0x1dff
	s_cbranch_scc1 .Ldp1_exit
	s_load_dwordx2 s[8:9], s[4:5], 0xf0
	v_bfe_u32 v0, v2, 5, 1
	v_and_b32_e32 v28, 31, v2
	v_bfe_u32 v1, v2, 3, 3
	v_lshlrev_b32_e32 v2, 3, v2
	v_and_b32_e32 v2, 56, v2
	v_mov_b32_e32 v3, 0
	v_mul_u32_u24_e32 v6, 0x84, v2
	v_lshlrev_b32_e32 v2, 1, v2
	s_mul_i32 s10, s6, 0x2200
	s_waitcnt lgkmcnt(0)
	v_lshl_add_u64 v[22:23], s[8:9], 0, v[2:3]
	s_mov_b64 s[6:7], 0x100000
	s_add_i32 s11, s10, 0
	v_lshl_add_u64 v[4:5], v[22:23], 0, s[6:7]
	v_lshlrev_b32_e32 v2, 2, v1
	s_mov_b64 s[6:7], 0xc00000
	v_add3_u32 v44, s11, v6, v2
	v_lshl_add_u64 v[6:7], v[22:23], 0, s[6:7]
	s_mov_b64 s[6:7], 0xe00000
	v_lshl_add_u64 v[8:9], v[22:23], 0, s[6:7]
	s_mov_b64 s[6:7], 0x1000000
	v_lshl_add_u64 v[10:11], v[22:23], 0, s[6:7]
	s_mov_b64 s[6:7], 0x1800000
	v_lshl_add_u64 v[12:13], v[22:23], 0, s[6:7]
	s_mov_b64 s[6:7], 0x2a00000
	v_lshl_add_u64 v[14:15], v[22:23], 0, s[6:7]
	s_mov_b64 s[6:7], 0x3200000
	v_lshl_add_u64 v[16:17], v[22:23], 0, s[6:7]
	s_mov_b64 s[6:7], 0x5e00000
	v_lshl_add_u64 v[18:19], v[22:23], 0, s[6:7]
	s_mov_b64 s[6:7], 0x8a00000
	v_mul_u32_u24_e32 v2, 0x84, v0
	v_lshl_add_u64 v[20:21], v[22:23], 0, s[6:7]
	s_mov_b64 s[6:7], 0xa000000
	v_or_b32_e32 v2, s10, v2
	v_lshlrev_b32_e32 v24, 2, v28
	v_or_b32_e32 v45, 8, v1
	v_or_b32_e32 v46, 16, v1
	v_or_b32_e32 v47, 24, v1
	v_lshl_add_u64 v[22:23], v[22:23], 0, s[6:7]
	v_add3_u32 v48, v2, v24, 0
	v_mov_b32_e32 v25, v3
	v_or_b32_e32 v49, 14, v0
	v_or_b32_e32 v50, 12, v0
	v_or_b32_e32 v51, 10, v0
	v_or_b32_e32 v52, 8, v0
	v_or_b32_e32 v53, 6, v0
	v_or_b32_e32 v54, 4, v0
	v_or_b32_e32 v55, 2, v0
	v_or_b32_e32 v26, 0x2c00000, v24
	v_mov_b32_e32 v27, v3
	s_movk_i32 s23, 0x2900
	s_movk_i32 s24, 0x7fff
	s_mov_b32 s25, 0xffff0000
	s_movk_i32 s26, 0x1800
	s_movk_i32 s27, 0x4800
	s_movk_i32 s28, 0x1600
	s_movk_i32 s29, 0x5800
	s_mov_b64 s[6:7], 0x2c00000
	v_lshlrev_b32_e32 v2, 2, v28
	v_mov_b32_e32 v56, 0x4800
	v_mov_b32_e32 v57, 0x5800
	s_branch .Ldp1_39
.Ldp1_38:
	s_add_i32 s99, s99, s33
	s_cmp_lt_i32 s99, 0x1e00
	s_cbranch_scc0 .Ldp1_exit
.Ldp1_39:
	s_add_i32 s22, s99, 0x69c0
	s_cmp_ge_i32 s99, 0x800
	s_cselect_b32 s98, 0x1600, 0
	s_add_i32 s22, s22, s98
	s_cmpk_gt_i32 s22, 0xa3f
	s_waitcnt lgkmcnt(0)
	s_cselect_b64 s[8:9], -1, 0
	s_cmpk_lt_i32 s22, 0xa40
	s_mov_b64 s[10:11], -1
	s_cbranch_scc0 .Ldp1_42
	s_andn2_b64 vcc, exec, s[10:11]
	s_cbranch_vccz .Ldp1_43

; #define LAS __attribute__((address_space(3)))
; __device__ __forceinline__ void p0_weights(KAP a, LAS unsigned char* lds, int gw, int NGW, int wave, int lane) {
;     LAS float* scr = (LAS float*)(lds + wave * 8704);
;     unsigned char* ws = a->ws;
;     constexpr int I_TOTAL = (2048 / 64) * (2624 / 32) + (512 / 64) * (1536 / 32) + (512 / 64) * (2048 / 32) + 2 * (2048 / 64) * (2048 / 32) + (2048 / 64) * (4608 / 32)
;                           + 4 * (2048 / 64) * (DFF / 32) + 2 * (DFF / 64) * (2048 / 32);
;     for (int item = gw; item < I_TOTAL; item += NGW) {
;         int it = item;
;         if (conv_matrix(it, a->in[13], 2048, 2624, (bf16*)(ws + WS_WIN0), 0, scr, lane)) continue;
;         if (conv_matrix(it, a->in[19], 512, 1536, (bf16*)(ws + WS_WUQ), 0, scr, lane, 0.07216878364870322f * 1.4426950408889634f)) continue;
;         if (conv_matrix(it, a->in[20], 512, 2048, (bf16*)(ws + WS_WUKV), 0, scr, lane)) continue;
;         if (conv_matrix(it, a->in[14], 2048, 2048, (bf16*)(ws + WS_WOUT0), 0, scr, lane)) continue;
;         if (conv_matrix(it, a->in[21], 2048, 4608, (bf16*)(ws + WS_WIN1), 0, scr, lane)) continue;
;         if (conv_matrix(it, a->in[22], 2048, 2048, (bf16*)(ws + WS_WOUT1), 0, scr, lane)) continue;
;         if (conv_matrix(it, a->in[10], 2048, DFF, (bf16*)(ws + WS_WGU), 1, scr, lane)) continue;
;         if (conv_matrix(it, a->in[10] + (size_t)2048 * DFF, 2048, DFF, (bf16*)(ws + WS_WGU + 44 * MiB), 1, scr, lane)) continue;
;         if (conv_matrix(it, a->in[11], 2048, DFF, (bf16*)(ws + WS_WGU), 2, scr, lane)) continue;
;         if (conv_matrix(it, a->in[11] + (size_t)2048 * DFF, 2048, DFF, (bf16*)(ws + WS_WGU + 44 * MiB), 2, scr, lane)) continue;
;         if (conv_matrix(it, a->in[12], DFF, 2048, (bf16*)(ws + WS_WD), 0, scr, lane)) continue;
;         conv_matrix(it, a->in[12] + (size_t)2048 * DFF, DFF, 2048, (bf16*)(ws + WS_WD + 22 * MiB), 0, scr, lane);
;     }
.Ldp2_36:
	v_mbcnt_lo_u32_b32 v2, -1, 0
	v_mbcnt_hi_u32_b32 v2, -1, v2
	s_sub_i32 s5, s87, 64
	s_lshl_b32 s5, s5, 3
	s_add_i32 s5, s5, 0x0
	v_readlane_b32 s4, v254, 48
	s_nop 1
	v_add_u32_e32 v0, s4, v2
	s_movk_i32 s33, 0x600
	v_readfirstlane_b32 s4, v0
	s_ashr_i32 s6, s4, 6
	s_add_i32 s99, s6, s5
	s_mov_b64 s[4:5], s[0:1]
	s_cmp_gt_i32 s99, 0x19ff
	s_cbranch_scc1 .Ldp2_exit
	s_load_dwordx2 s[8:9], s[4:5], 0xf0
	v_bfe_u32 v0, v2, 5, 1
	v_and_b32_e32 v28, 31, v2
	v_bfe_u32 v1, v2, 3, 3
	v_lshlrev_b32_e32 v2, 3, v2
	v_and_b32_e32 v2, 56, v2
	v_mov_b32_e32 v3, 0
	v_mul_u32_u24_e32 v6, 0x84, v2
	v_lshlrev_b32_e32 v2, 1, v2
	s_mul_i32 s10, s6, 0x2200
	s_waitcnt lgkmcnt(0)
	v_lshl_add_u64 v[22:23], s[8:9], 0, v[2:3]
	s_mov_b64 s[6:7], 0x100000
	s_add_i32 s11, s10, 0
	v_lshl_add_u64 v[4:5], v[22:23], 0, s[6:7]
	v_lshlrev_b32_e32 v2, 2, v1
	s_mov_b64 s[6:7], 0xc00000
	v_add3_u32 v44, s11, v6, v2
	v_lshl_add_u64 v[6:7], v[22:23], 0, s[6:7]
	s_mov_b64 s[6:7], 0xe00000
	v_lshl_add_u64 v[8:9], v[22:23], 0, s[6:7]
	s_mov_b64 s[6:7], 0x1000000
	v_lshl_add_u64 v[10:11], v[22:23], 0, s[6:7]
	s_mov_b64 s[6:7], 0x1800000
	v_lshl_add_u64 v[12:13], v[22:23], 0, s[6:7]
	s_mov_b64 s[6:7], 0x2a00000
	v_lshl_add_u64 v[14:15], v[22:23], 0, s[6:7]
	s_mov_b64 s[6:7], 0x3200000
	v_lshl_add_u64 v[16:17], v[22:23], 0, s[6:7]
	s_mov_b64 s[6:7], 0x5e00000
	v_lshl_add_u64 v[18:19], v[22:23], 0, s[6:7]
	s_mov_b64 s[6:7], 0x8a00000
	v_mul_u32_u24_e32 v2, 0x84, v0
	v_lshl_add_u64 v[20:21], v[22:23], 0, s[6:7]
	s_mov_b64 s[6:7], 0xa000000
	v_or_b32_e32 v2, s10, v2
	v_lshlrev_b32_e32 v24, 2, v28
	v_or_b32_e32 v45, 8, v1
	v_or_b32_e32 v46, 16, v1
	v_or_b32_e32 v47, 24, v1
	v_lshl_add_u64 v[22:23], v[22:23], 0, s[6:7]
	v_add3_u32 v48, v2, v24, 0
	v_mov_b32_e32 v25, v3
	v_or_b32_e32 v49, 14, v0
	v_or_b32_e32 v50, 12, v0
	v_or_b32_e32 v51, 10, v0
	v_or_b32_e32 v52, 8, v0
	v_or_b32_e32 v53, 6, v0
	v_or_b32_e32 v54, 4, v0
	v_or_b32_e32 v55, 2, v0
	v_or_b32_e32 v26, 0x2c00000, v24
	v_mov_b32_e32 v27, v3
	s_movk_i32 s23, 0x2900
	s_movk_i32 s24, 0x7fff
	s_mov_b32 s25, 0xffff0000
	s_movk_i32 s26, 0x1800
	s_movk_i32 s27, 0x4800
	s_movk_i32 s28, 0x1600
	s_movk_i32 s29, 0x5800
	s_mov_b64 s[6:7], 0x2c00000
	v_lshlrev_b32_e32 v2, 2, v28
	v_mov_b32_e32 v56, 0x4800
	v_mov_b32_e32 v57, 0x5800
	s_branch .Ldp2_39
.Ldp2_38:
	s_add_i32 s99, s99, s33
	s_cmp_lt_i32 s99, 0x1a00
	s_cbranch_scc0 .Ldp2_exit
.Ldp2_39:
	s_add_i32 s22, s99, 0x15c0
	s_cmpk_gt_i32 s22, 0xa3f
	s_waitcnt lgkmcnt(0)
	s_cselect_b64 s[8:9], -1, 0
	s_cmpk_lt_i32 s22, 0xa40
	s_mov_b64 s[10:11], -1
	s_cbranch_scc0 .Ldp2_42
	s_andn2_b64 vcc, exec, s[10:11]
	s_cbranch_vccz .Ldp2_43

; __device__ __forceinline__ void xcd_barrier(const XcdBarrier& b) {
;     asm volatile("s_waitcnt vmcnt(0)" ::: "memory");
;     __syncthreads();
;     if (threadIdx.x == 0) {
.Ldp2_exit:
	v_readlane_b32 s10, v255, 10
	v_readlane_b32 s12, v255, 11
	v_readlane_b32 s13, v255, 12
	v_readlane_b32 s14, v255, 13
	v_readlane_b32 s15, v255, 14
	v_readlane_b32 s22, v255, 15
	v_readlane_b32 s23, v255, 16
	v_readlane_b32 s24, v255, 17
	v_readlane_b32 s25, v255, 18
	v_readlane_b32 s26, v255, 19
	v_readlane_b32 s27, v255, 20
	v_readlane_b32 s28, v255, 21
	v_readlane_b32 s29, v255, 22
	v_readlane_b32 s31, v255, 23
	v_readlane_b32 s33, v255, 24
	v_mov_b32_e32 v3, v250
	s_nop 3
.Ldp2_skip:
	s_waitcnt vmcnt(0)
	s_barrier
	s_mov_b64 s[16:17], exec
	v_readlane_b32 s4, v253, 0
	v_readlane_b32 s5, v253, 1
	s_and_b64 s[4:5], s[16:17], s[4:5]
	s_mov_b64 exec, s[4:5]
	s_cbranch_execnz .LBB0_1228
	s_getpc_b64 s[98:99]
